# attention prologue: first-chunk K/V loads issued with the Q loads
# baseline (speedup 1.0000x reference)
.LBB0_396:
	s_waitcnt vmcnt(0)
	s_barrier
	v_readlane_b32 s3, v254, 20
	v_readlane_b32 s2, v254, 4
	s_add_i32 s0, s3, 1
	s_lshr_b32 s2, s2, 3
	s_lshl_b32 s3, s3, 5
	v_writelane_b32 v254, s0, 20
	s_add_i32 s3, s3, s2
	v_mov_b32_e32 v0, s3
	s_movk_i32 s0, 0x7f
	s_waitcnt lgkmcnt(0)
	v_cmp_lt_i32_e32 vcc, s0, v0
	s_mov_b64 s[0:1], -1
	s_cbranch_vccnz .LBB0_395
	v_mov_b32_e32 v96, v193
	s_add_i32 s0, s3, s69
	s_bfe_u32 s2, s3, 0x10005
	v_readfirstlane_b32 s1, v96
	s_ashr_i32 s4, s0, 6
	s_and_b32 s72, s3, 31
	s_ashr_i32 s0, s1, 7
	s_lshl_b32 s3, s2, 2
	s_add_i32 s0, s0, s3
	v_bfe_u32 v97, v96, 5, 1
	s_bfe_u32 s7, s1, 0x10006
	s_lshl_b32 s36, s0, 6
	s_lshl_b32 s1, s72, 7
	s_lshl_b32 s6, s7, 6
	s_ashr_i32 s37, s36, 31
	v_lshlrev_b32_e32 v40, 3, v97
	s_or_b32 s70, s6, s1
	s_lshl_b32 s71, s4, 12
	s_lshl_b64 s[36:37], s[36:37], 1
	v_cvt_f32_ubyte0_e32 v9, v40
	v_and_b32_e32 v222, 31, v96
	s_add_u32 s52, s28, s36
	v_cmp_lt_i32_e32 vcc, v208, v209
	v_mul_f32_e32 v10, 0xbf549a78, v9
	v_or_b32_e32 v80, s70, v222
	s_addc_u32 s53, s29, s37
	v_lshlrev_b32_e32 v198, 4, v97
	v_cndmask_b32_e32 v0, v207, v208, vcc
	v_cmp_gt_f32_e32 vcc, s30, v10
	v_lshl_add_u64 v[56:57], s[52:53], 0, v[198:199]
	v_lshlrev_b32_e32 v221, 2, v0
	v_or_b32_e32 v0, s71, v80
	v_cndmask_b32_e32 v10, 0, v213, vcc
	v_mad_i64_i32 v[0:1], s[52:53], v0, s25, v[56:57]
	v_and_b32_e32 v8, 32, v96
	v_fmac_f32_e32 v10, 0xbf549a78, v9
	s_lshl_b32 s98, s4, 8
	s_add_i32 s98, s98, 0x10000
	v_lshrrev_b32_e32 v238, 2, v193
	v_add_u32_e32 v238, s98, v238
	v_mov_b64_e32 v[240:241], s[28:29]
	v_mad_u64_u32 v[240:241], s[100:101], v238, s25, v[240:241]
	s_lshl_b32 s98, s2, 7
	s_mov_b32 s99, 0
	v_lshl_add_u64 v[240:241], v[240:241], 0, s[98:99]
	v_bfe_u32 v242, v193, 1, 1
	v_mov_b32_e32 v243, 0
	v_lshlrev_b32_e32 v242, 6, v242
	v_lshl_add_u64 v[244:245], v[240:241], 0, v[242:243]
	v_and_b32_e32 v242, 1, v193
	v_lshlrev_b32_e32 v242, 4, v242
	v_lshl_add_u64 v[244:245], v[244:245], 0, v[242:243]
	v_and_b32_e32 v242, 3, v193
	v_lshlrev_b32_e32 v242, 5, v242
	v_lshl_add_u64 v[246:247], v[240:241], 0, v[242:243]
	global_load_dwordx4 v[176:179], v[244:245], off offset:1024
	global_load_dwordx4 v[180:183], v[244:245], off offset:1056
	global_load_dwordx4 v[184:187], v[246:247], off offset:1296
	global_load_dwordx4 v[188:191], v[246:247], off offset:1280
	global_load_dwordx4 v[24:27], v[0:1], off
	global_load_dwordx4 v[28:31], v[0:1], off offset:32
	global_load_dwordx4 v[88:91], v[0:1], off offset:64
	global_load_dwordx4 v[92:95], v[0:1], off offset:96
	global_load_dwordx4 v[16:19], v8, s[14:15]
	global_load_dwordx4 v[20:23], v8, s[14:15] offset:16
	global_load_dwordx4 v[4:7], v8, s[14:15] offset:64
	s_nop 0
	global_load_dwordx4 v[0:3], v8, s[14:15] offset:80
	global_load_dwordx4 v[100:103], v8, s[14:15] offset:128
	global_load_dwordx4 v[52:55], v8, s[14:15] offset:144
	v_exp_f32_e32 v32, v10
	global_load_dwordx4 v[12:15], v8, s[14:15] offset:192
	s_nop 0
	global_load_dwordx4 v[8:11], v8, s[14:15] offset:208
	v_cndmask_b32_e32 v33, 0, v214, vcc
	s_lshr_b32 s1, s70, 6
	v_ldexp_f32 v81, v32, v33
	v_or_b32_e32 v33, 1, v40
	v_cvt_f32_ubyte0_e32 v33, v33
	v_mul_f32_e32 v34, 0xbf549a78, v33
	v_cmp_gt_f32_e32 vcc, s30, v34
	v_cvt_f32_ubyte0_e32 v41, s1
	v_mul_f32_e32 v32, v81, v41
	v_cndmask_b32_e32 v34, 0, v213, vcc
	v_fmac_f32_e32 v34, 0xbf549a78, v33
	v_cvt_f32_ubyte0_e32 v50, v222
	v_mul_f32_e32 v32, 0.15915494, v32
	v_exp_f32_e32 v33, v34
	v_sin_f32_e32 v42, v32
	v_cos_f32_e32 v43, v32
	v_mul_f32_e32 v32, v81, v50
	v_mul_f32_e32 v32, 0.15915494, v32
	v_sin_f32_e32 v62, v32
	v_cos_f32_e32 v63, v32
	v_cndmask_b32_e32 v32, 0, v214, vcc
	v_ldexp_f32 v82, v33, v32
	v_or_b32_e32 v33, 2, v40
	v_cvt_f32_ubyte0_e32 v33, v33
	v_mul_f32_e32 v34, 0xbf549a78, v33
	v_cmp_gt_f32_e32 vcc, s30, v34
	v_mul_f32_e32 v32, v82, v41
	v_mul_f32_e32 v32, 0.15915494, v32
	v_cndmask_b32_e32 v34, 0, v213, vcc
	v_fmac_f32_e32 v34, 0xbf549a78, v33
	v_exp_f32_e32 v33, v34
	v_sin_f32_e32 v45, v32
	v_cos_f32_e32 v44, v32
	v_mul_f32_e32 v32, v82, v50
	v_mul_f32_e32 v32, 0.15915494, v32
	v_sin_f32_e32 v65, v32
	v_cos_f32_e32 v64, v32
	v_cndmask_b32_e32 v32, 0, v214, vcc
	v_ldexp_f32 v83, v33, v32
	v_or_b32_e32 v33, 3, v40
	v_cvt_f32_ubyte0_e32 v33, v33
	v_mul_f32_e32 v34, 0xbf549a78, v33
	v_mul_f32_e32 v32, v83, v41
	v_cmp_gt_f32_e32 vcc, s30, v34
	v_mul_f32_e32 v32, 0.15915494, v32
	v_or_b32_e32 v35, 4, v40
	v_cndmask_b32_e32 v34, 0, v213, vcc
	v_sin_f32_e32 v46, v32
	v_cos_f32_e32 v47, v32
	v_mul_f32_e32 v32, v83, v50
	v_fmac_f32_e32 v34, 0xbf549a78, v33
	v_cvt_f32_ubyte0_e32 v35, v35
	v_mul_f32_e32 v32, 0.15915494, v32
	v_exp_f32_e32 v33, v34
	v_mul_f32_e32 v36, 0xbf549a78, v35
	v_sin_f32_e32 v70, v32
	v_cos_f32_e32 v71, v32
	v_cndmask_b32_e32 v32, 0, v214, vcc
	v_cmp_gt_f32_e32 vcc, s30, v36
	v_ldexp_f32 v84, v33, v32
	v_or_b32_e32 v37, 5, v40
	v_cndmask_b32_e32 v36, 0, v213, vcc
	v_fmac_f32_e32 v36, 0xbf549a78, v35
	v_exp_f32_e32 v35, v36
	v_mul_f32_e32 v34, v84, v50
	v_cvt_f32_ubyte0_e32 v37, v37
	v_mul_f32_e32 v34, 0.15915494, v34
	v_mul_f32_e32 v38, 0xbf549a78, v37
	v_sin_f32_e32 v73, v34
	v_cos_f32_e32 v72, v34
	v_cndmask_b32_e32 v34, 0, v214, vcc
	v_cmp_gt_f32_e32 vcc, s30, v38
	v_ldexp_f32 v85, v35, v34
	v_or_b32_e32 v39, 6, v40
	v_cndmask_b32_e32 v38, 0, v213, vcc
	v_mul_f32_e32 v36, v85, v50
	v_fmac_f32_e32 v38, 0xbf549a78, v37
	v_cvt_f32_ubyte0_e32 v39, v39
	v_mul_f32_e32 v36, 0.15915494, v36
	v_exp_f32_e32 v37, v38
	v_mul_f32_e32 v48, 0xbf549a78, v39
	v_sin_f32_e32 v74, v36
	v_cos_f32_e32 v75, v36
	v_cndmask_b32_e32 v36, 0, v214, vcc
	v_cmp_gt_f32_e32 vcc, s30, v48
	v_ldexp_f32 v86, v37, v36
	v_mul_f32_e32 v38, v86, v50
	v_cndmask_b32_e32 v48, 0, v213, vcc
	v_fmac_f32_e32 v48, 0xbf549a78, v39
	v_exp_f32_e32 v39, v48
	v_mul_f32_e32 v38, 0.15915494, v38
	v_sin_f32_e32 v77, v38
	v_cos_f32_e32 v76, v38
	v_cndmask_b32_e32 v38, 0, v214, vcc
	v_ldexp_f32 v87, v39, v38
	v_mul_f32_e32 v48, v87, v50
	v_or_b32_e32 v40, 7, v40
	v_mul_f32_e32 v48, 0.15915494, v48
	v_cvt_f32_ubyte0_e32 v40, v40
	v_sin_f32_e32 v66, v48
	v_cos_f32_e32 v67, v48
	v_mul_f32_e32 v48, 0xbf549a78, v40
	v_cmp_gt_f32_e32 vcc, s30, v48
	s_waitcnt vmcnt(0)
	v_mov_b32_e32 v49, v10
	v_lshlrev_b32_e32 v60, 16, v91
	v_cndmask_b32_e32 v48, 0, v213, vcc
	v_fmac_f32_e32 v48, 0xbf549a78, v40
	v_exp_f32_e32 v40, v48
	v_cndmask_b32_e32 v10, 0, v214, vcc
	v_and_b32_e32 v104, 0xffff0000, v91
	v_mul_f32_e32 v32, v84, v41
	v_ldexp_f32 v99, v40, v10
	v_mul_f32_e32 v10, v99, v41
	v_mul_f32_e32 v10, 0.15915494, v10
	v_mul_f32_e32 v34, v85, v41
	v_mul_f32_e32 v36, v86, v41
	v_mul_f32_e32 v38, v87, v41
	v_lshlrev_b32_e32 v61, 16, v95
	v_sin_f32_e32 v41, v10
	v_cos_f32_e32 v40, v10
	v_mul_f32_e32 v10, v99, v50
	v_and_b32_e32 v105, 0xffff0000, v95
	v_mov_b32_e32 v50, v104
	v_mov_b32_e32 v51, v60
	v_pk_mul_f32 v[106:107], v[50:51], v[50:51]
	v_mov_b32_e32 v50, v105
	v_mov_b32_e32 v51, v61
	v_pk_mul_f32 v[108:109], v[50:51], v[50:51]
	v_mov_b32_e32 v51, v8
	v_mov_b32_e32 v8, v53
	v_lshlrev_b32_e32 v112, 16, v89
	v_mov_b32_e32 v53, v14
	v_and_b32_e32 v114, 0xffff0000, v89
	v_mov_b32_e32 v14, v103
	v_lshlrev_b32_e32 v103, 16, v92
	v_and_b32_e32 v89, 0xffff0000, v92
	v_lshlrev_b32_e32 v140, 16, v25
	v_and_b32_e32 v144, 0xffff0000, v25
	v_lshlrev_b32_e32 v149, 16, v28
	v_lshlrev_b32_e32 v148, 16, v24
	v_and_b32_e32 v25, 0xffff0000, v28
	v_and_b32_e32 v24, 0xffff0000, v24
	v_mov_b32_e32 v58, v89
	v_mov_b32_e32 v59, v103
	v_lshlrev_b32_e32 v141, 16, v29
	v_and_b32_e32 v145, 0xffff0000, v29
	v_pk_mul_f32 v[150:151], v[148:149], v[148:149]
	v_pk_mul_f32 v[28:29], v[24:25], v[24:25]
	v_lshlrev_b32_e32 v113, 16, v93
	v_and_b32_e32 v115, 0xffff0000, v93
	v_pk_mul_f32 v[92:93], v[58:59], v[58:59]
	v_mov_b32_e32 v58, v22
	v_mov_b32_e32 v22, v20
	v_pk_mul_f32 v[142:143], v[140:141], v[140:141]
	v_add_f32_e32 v20, v150, v28
	v_lshlrev_b32_e32 v137, 16, v30
	v_lshlrev_b32_e32 v136, 16, v26
	v_pk_mul_f32 v[146:147], v[144:145], v[144:145]
	v_add_f32_e32 v20, v142, v20
	v_lshlrev_b32_e32 v128, 16, v27
	v_and_b32_e32 v132, 0xffff0000, v27
	v_pk_mul_f32 v[138:139], v[136:137], v[136:137]
	v_and_b32_e32 v27, 0xffff0000, v30
	v_and_b32_e32 v26, 0xffff0000, v26
	v_add_f32_e32 v20, v146, v20
	v_lshlrev_b32_e32 v129, 16, v31
	v_and_b32_e32 v133, 0xffff0000, v31
	v_pk_mul_f32 v[30:31], v[26:27], v[26:27]
	v_add_f32_e32 v20, v138, v20
	v_pk_mul_f32 v[130:131], v[128:129], v[128:129]
	v_add_f32_e32 v20, v30, v20
	v_pk_mul_f32 v[134:135], v[132:133], v[132:133]
	v_add_f32_e32 v20, v130, v20
	v_add_f32_e32 v20, v134, v20
	v_add_f32_e32 v20, v151, v20
	v_add_f32_e32 v20, v29, v20
	v_add_f32_e32 v20, v143, v20
	v_add_f32_e32 v20, v147, v20
	v_add_f32_e32 v20, v139, v20
	v_add_f32_e32 v20, v31, v20
	v_add_f32_e32 v20, v131, v20
	v_mov_b32_e32 v50, v52
	v_mov_b32_e32 v52, v102
	v_lshlrev_b32_e32 v102, 16, v88
	v_add_f32_e32 v20, v135, v20
	v_and_b32_e32 v88, 0xffff0000, v88
	v_fmac_f32_e32 v20, v102, v102
	v_fmac_f32_e32 v20, v88, v88
	v_fmac_f32_e32 v20, v112, v112
	v_lshlrev_b32_e32 v110, 16, v90
	v_fmac_f32_e32 v20, v114, v114
	v_and_b32_e32 v90, 0xffff0000, v90
	v_fmac_f32_e32 v20, v110, v110
	v_fmac_f32_e32 v20, v90, v90
	v_mul_f32_e32 v10, 0.15915494, v10
	v_lshlrev_b32_e32 v111, 16, v94
	v_and_b32_e32 v91, 0xffff0000, v94
	v_add_f32_e32 v20, v107, v20
	v_mov_b32_e32 v48, v54
	v_sin_f32_e32 v69, v10
	v_cos_f32_e32 v68, v10
	v_mov_b32_e32 v10, v55
	v_mov_b32_e32 v54, v91
	v_mov_b32_e32 v55, v111
	v_add_f32_e32 v20, v106, v20
	v_pk_mul_f32 v[94:95], v[54:55], v[54:55]
	v_mov_b32_e32 v54, v115
	v_mov_b32_e32 v55, v113
	v_add_f32_e32 v20, v93, v20
	v_pk_mul_f32 v[116:117], v[54:55], v[54:55]
	v_add_f32_e32 v20, v92, v20
	v_add_f32_e32 v20, v117, v20
	v_add_f32_e32 v20, v116, v20
	v_add_f32_e32 v20, v95, v20
	v_add_f32_e32 v20, v94, v20
	v_add_f32_e32 v20, v109, v20
	v_add_f32_e32 v20, v108, v20
	ds_bpermute_b32 v30, v221, v20
	v_mov_b32_e32 v29, v6
	v_mov_b32_e32 v28, v18
	v_mov_b32_e32 v31, v4
	v_mov_b32_e32 v54, v100
	s_waitcnt lgkmcnt(0)
	v_add_f32_e32 v6, v20, v30
	v_fmamk_f32 v6, v6, 0x3c800000, v211
	v_mul_f32_e32 v18, 0x4b800000, v6
	v_cmp_gt_f32_e32 vcc, s33, v6
	v_mov_b32_e32 v55, v12
	v_mov_b32_e32 v30, v16
	v_cndmask_b32_e32 v6, v6, v18, vcc
	v_rsq_f32_e32 v18, v6
	v_mov_b32_e32 v12, v101
	v_mov_b32_e32 v59, v2
	v_mov_b32_e32 v2, v23
	v_mul_f32_e32 v4, 0x45800000, v18
	v_cndmask_b32_e32 v16, v18, v4, vcc
	v_pk_mul_f32 v[116:117], v[54:55], v[16:17] op_sel_hi:[1,0]
	v_mov_b32_e32 v23, v0
	v_pk_mul_f32 v[102:103], v[116:117], v[102:103]
	v_pk_mul_f32 v[116:117], v[12:13], v[16:17] op_sel_hi:[1,0]
	v_mov_b32_e32 v0, v21
	v_pk_mul_f32 v[88:89], v[116:117], v[88:89]
	v_pk_mul_f32 v[116:117], v[52:53], v[16:17] op_sel_hi:[1,0]
	v_mov_b32_e32 v4, v17
	v_pk_mul_f32 v[112:113], v[116:117], v[112:113]
	v_pk_mul_f32 v[116:117], v[14:15], v[16:17] op_sel_hi:[1,0]
	v_mov_b32_e32 v6, v19
	v_pk_mul_f32 v[114:115], v[116:117], v[114:115]
	v_pk_mul_f32 v[116:117], v[50:51], v[16:17] op_sel_hi:[1,0]
	v_pk_mul_f32 v[18:19], v[30:31], v[16:17] op_sel_hi:[1,0]
	v_pk_mul_f32 v[110:111], v[116:117], v[110:111]
	v_pk_mul_f32 v[116:117], v[8:9], v[16:17] op_sel_hi:[1,0]
	v_pk_mul_f32 v[20:21], v[4:5], v[16:17] op_sel_hi:[1,0]
	v_pk_mul_f32 v[106:107], v[0:1], v[16:17] op_sel_hi:[1,0]
	v_pk_mul_f32 v[90:91], v[116:117], v[90:91]
	v_pk_mul_f32 v[116:117], v[48:49], v[16:17] op_sel_hi:[1,0]
	v_pk_mul_f32 v[18:19], v[18:19], v[148:149]
	v_pk_mul_f32 v[20:21], v[20:21], v[24:25]
	v_pk_mul_f32 v[24:25], v[28:29], v[16:17] op_sel_hi:[1,0]
	v_pk_mul_f32 v[92:93], v[6:7], v[16:17] op_sel_hi:[1,0]
	v_pk_mul_f32 v[94:95], v[22:23], v[16:17] op_sel_hi:[1,0]
	v_pk_mul_f32 v[26:27], v[106:107], v[26:27]
	v_pk_mul_f32 v[106:107], v[58:59], v[16:17] op_sel_hi:[1,0]
	v_pk_mul_f32 v[108:109], v[2:3], v[16:17] op_sel_hi:[1,0]
	v_pk_mul_f32 v[116:117], v[116:117], v[60:61]
	v_pk_mul_f32 v[16:17], v[10:11], v[16:17] op_sel_hi:[1,0]
	v_mov_b32_e32 v60, v43
	v_mov_b32_e32 v61, v42
	v_pk_mul_f32 v[104:105], v[16:17], v[104:105]
	v_pk_mul_f32 v[16:17], v[60:61], v[18:19]
	v_pk_mul_f32 v[106:107], v[106:107], v[128:129]
	v_sub_f32_e32 v16, v16, v17
	v_mul_f32_e32 v128, 0x3e38aa3b, v16
	v_pk_mul_f32 v[16:17], v[42:43], v[18:19]
	v_mov_b32_e32 v100, v63
	v_mov_b32_e32 v101, v62
	v_add_f32_e32 v16, v16, v17
	v_pk_mul_f32 v[108:109], v[108:109], v[132:133]
	v_mul_f32_e32 v132, 0x3e38aa3b, v16
	v_pk_mul_f32 v[16:17], v[100:101], v[102:103]
	v_pk_mul_f32 v[24:25], v[24:25], v[140:141]
	v_sub_f32_e32 v16, v16, v17
	v_mul_f32_e32 v100, 0x3e38aa3b, v16
	v_pk_mul_f32 v[16:17], v[62:63], v[102:103]
	v_mov_b32_e32 v62, v45
	v_add_f32_e32 v16, v16, v17
	v_mul_f32_e32 v140, 0x3e38aa3b, v16
	v_pk_mul_f32 v[16:17], v[44:45], v[20:21]
	v_mov_b32_e32 v63, v44
	v_sub_f32_e32 v16, v16, v17
	v_mul_f32_e32 v101, 0x3e38aa3b, v16
	v_pk_mul_f32 v[16:17], v[62:63], v[20:21]
	v_mov_b32_e32 v118, v65
	v_add_f32_e32 v16, v16, v17
	v_mul_f32_e32 v102, 0x3e38aa3b, v16
	v_pk_mul_f32 v[16:17], v[64:65], v[88:89]
	v_mov_b32_e32 v119, v64
	v_sub_f32_e32 v16, v16, v17
	v_mul_f32_e32 v103, 0x3e38aa3b, v16
	v_pk_mul_f32 v[16:17], v[118:119], v[88:89]
	v_mov_b32_e32 v64, v47
	v_add_f32_e32 v16, v16, v17
	v_mov_b32_e32 v65, v46
	v_mul_f32_e32 v118, 0x3e38aa3b, v16
	v_pk_mul_f32 v[16:17], v[64:65], v[24:25]
	v_mul_f32_e32 v32, 0.15915494, v32
	v_sub_f32_e32 v16, v16, v17
	v_mul_f32_e32 v119, 0x3e38aa3b, v16
	v_pk_mul_f32 v[16:17], v[46:47], v[24:25]
	v_mov_b32_e32 v120, v71
	v_mov_b32_e32 v121, v70
	v_add_f32_e32 v16, v16, v17
	v_sin_f32_e32 v33, v32
	v_cos_f32_e32 v32, v32
	v_mul_f32_e32 v133, 0x3e38aa3b, v16
	v_pk_mul_f32 v[16:17], v[120:121], v[112:113]
	v_pk_mul_f32 v[92:93], v[92:93], v[144:145]
	v_sub_f32_e32 v16, v16, v17
	v_mul_f32_e32 v120, 0x3e38aa3b, v16
	v_pk_mul_f32 v[16:17], v[70:71], v[112:113]
	v_mul_f32_e32 v35, 0.15915494, v34
	v_add_f32_e32 v16, v16, v17
	v_mul_f32_e32 v70, 0x3e38aa3b, v16
	v_pk_mul_f32 v[16:17], v[32:33], v[92:93]
	v_sin_f32_e32 v34, v35
	v_sub_f32_e32 v16, v16, v17
	v_mul_f32_e32 v71, 0x3e38aa3b, v16
	v_mov_b32_e32 v16, v33
	v_mov_b32_e32 v17, v32
	v_pk_mul_f32 v[18:19], v[16:17], v[92:93]
	v_cos_f32_e32 v35, v35
	v_add_f32_e32 v18, v18, v19
	v_mul_f32_e32 v112, 0x3e38aa3b, v18
	v_pk_mul_f32 v[18:19], v[72:73], v[114:115]
	v_mov_b32_e32 v122, v73
	v_mov_b32_e32 v123, v72
	v_sub_f32_e32 v18, v18, v19
	v_mul_f32_e32 v72, 0x3e38aa3b, v18
	v_pk_mul_f32 v[18:19], v[122:123], v[114:115]
	v_pk_mul_f32 v[94:95], v[94:95], v[136:137]
	v_add_f32_e32 v18, v18, v19
	v_mul_f32_e32 v73, 0x3e38aa3b, v18
	v_mov_b32_e32 v18, v35
	v_mov_b32_e32 v19, v34
	v_pk_mul_f32 v[20:21], v[18:19], v[94:95]
	v_mul_f32_e32 v36, 0.15915494, v36
	v_sub_f32_e32 v20, v20, v21
	v_mul_f32_e32 v113, 0x3e38aa3b, v20
	v_pk_mul_f32 v[20:21], v[34:35], v[94:95]
	v_mov_b32_e32 v124, v75
	v_mov_b32_e32 v125, v74
	v_add_f32_e32 v20, v20, v21
	v_sin_f32_e32 v37, v36
	v_cos_f32_e32 v36, v36
	v_mul_f32_e32 v114, 0x3e38aa3b, v20
	v_pk_mul_f32 v[20:21], v[124:125], v[110:111]
	v_mul_f32_e32 v39, 0.15915494, v38
	v_sub_f32_e32 v20, v20, v21
	v_mul_f32_e32 v115, 0x3e38aa3b, v20
	v_pk_mul_f32 v[20:21], v[74:75], v[110:111]
	v_sin_f32_e32 v38, v39
	v_add_f32_e32 v20, v20, v21
	v_mul_f32_e32 v74, 0x3e38aa3b, v20
	v_pk_mul_f32 v[20:21], v[36:37], v[26:27]
	v_cos_f32_e32 v39, v39
	v_sub_f32_e32 v20, v20, v21
	v_mul_f32_e32 v75, 0x3e38aa3b, v20
	v_mov_b32_e32 v20, v37
	v_mov_b32_e32 v21, v36
	v_pk_mul_f32 v[24:25], v[20:21], v[26:27]
	v_mov_b32_e32 v126, v77
	v_add_f32_e32 v24, v24, v25
	v_mul_f32_e32 v110, 0x3e38aa3b, v24
	v_pk_mul_f32 v[24:25], v[76:77], v[90:91]
	v_mov_b32_e32 v127, v76
	v_sub_f32_e32 v24, v24, v25
	v_mul_f32_e32 v76, 0x3e38aa3b, v24
	v_pk_mul_f32 v[24:25], v[126:127], v[90:91]
	v_mov_b32_e32 v78, v67
	v_add_f32_e32 v24, v24, v25
	v_or_b32_e32 v25, 32, v80
	v_or_b32_e32 v25, s71, v25
	v_mad_i64_i32 v[56:57], s[52:53], v25, s25, v[56:57]
	v_mul_f32_e32 v77, 0x3e38aa3b, v24
	v_mov_b32_e32 v24, v39
	v_mov_b32_e32 v25, v38
	v_pk_mul_f32 v[26:27], v[24:25], v[106:107]
	v_mov_b32_e32 v79, v66
	v_sub_f32_e32 v26, v26, v27
	v_mul_f32_e32 v111, 0x3e38aa3b, v26
	v_pk_mul_f32 v[26:27], v[38:39], v[106:107]
	global_load_dwordx4 v[88:91], v[56:57], off offset:64
	global_load_dwordx4 v[92:95], v[56:57], off offset:96
	v_add_f32_e32 v26, v26, v27
	v_mul_f32_e32 v106, 0x3e38aa3b, v26
	v_pk_mul_f32 v[26:27], v[78:79], v[116:117]
	v_cvt_pk_bf16_f32 v128, v128, v101
	v_cvt_pk_bf16_f32 v132, v132, v102
	v_cvt_pk_bf16_f32 v136, v100, v103
	v_cvt_pk_bf16_f32 v130, v113, v75
	v_cvt_pk_bf16_f32 v142, v74, v77
	s_nop 0
	v_sub_f32_e32 v26, v26, v27
	v_mul_f32_e32 v78, 0x3e38aa3b, v26
	v_pk_mul_f32 v[26:27], v[66:67], v[116:117]
	v_cvt_pk_bf16_f32 v137, v120, v72
	v_cvt_pk_bf16_f32 v141, v70, v73
	v_cvt_pk_bf16_f32 v129, v119, v71
	v_cvt_pk_bf16_f32 v138, v115, v76
	v_cvt_pk_bf16_f32 v134, v114, v110
	s_nop 0
	v_add_f32_e32 v26, v26, v27
	v_mul_f32_e32 v79, 0x3e38aa3b, v26
	v_pk_mul_f32 v[26:27], v[40:41], v[108:109]
	v_cvt_pk_bf16_f32 v140, v140, v118
	v_cvt_pk_bf16_f32 v133, v133, v112
	v_and_b32_e32 v98, 63, v96
	v_sub_f32_e32 v26, v26, v27
	v_mul_f32_e32 v107, 0x3e38aa3b, v26
	v_mov_b32_e32 v26, v41
	v_mov_b32_e32 v27, v40
	v_pk_mul_f32 v[66:67], v[26:27], v[108:109]
	v_cvt_pk_bf16_f32 v131, v111, v107
	s_ashr_i32 s1, s0, 31
	v_add_f32_e32 v66, v66, v67
	v_mul_f32_e32 v108, 0x3e38aa3b, v66
	v_pk_mul_f32 v[66:67], v[68:69], v[104:105]
	v_cvt_pk_bf16_f32 v135, v106, v108
	s_lshl_b64 s[0:1], s[0:1], 2
	v_sub_f32_e32 v66, v66, v67
	v_mul_f32_e32 v109, 0x3e38aa3b, v66
	v_mov_b32_e32 v66, v69
	v_mov_b32_e32 v67, v68
	v_pk_mul_f32 v[66:67], v[66:67], v[104:105]
	global_load_dwordx4 v[100:103], v[56:57], off
	global_load_dwordx4 v[104:107], v[56:57], off offset:32
	v_bitop3_b32 v56, v80, 63, 32 bitop3:0xc8
	v_cvt_f32_ubyte0_e32 v56, v56
	v_mul_f32_e32 v57, v81, v56
	v_mul_f32_e32 v57, 0.15915494, v57
	v_sin_f32_e32 v80, v57
	v_cos_f32_e32 v81, v57
	v_mul_f32_e32 v57, v82, v56
	v_mul_f32_e32 v57, 0.15915494, v57
	v_cvt_pk_bf16_f32 v139, v78, v109
	v_sin_f32_e32 v109, v57
	v_cos_f32_e32 v108, v57
	v_mul_f32_e32 v57, v83, v56
	v_mul_f32_e32 v57, 0.15915494, v57
	v_sin_f32_e32 v74, v57
	v_cos_f32_e32 v75, v57
	v_mul_f32_e32 v57, v84, v56
	v_mul_f32_e32 v57, 0.15915494, v57
	v_sin_f32_e32 v73, v57
	v_cos_f32_e32 v72, v57
	v_mul_f32_e32 v57, v85, v56
	v_mul_f32_e32 v57, 0.15915494, v57
	v_sin_f32_e32 v70, v57
	v_cos_f32_e32 v71, v57
	v_mul_f32_e32 v57, v86, v56
	v_mul_f32_e32 v57, 0.15915494, v57
	v_sin_f32_e32 v69, v57
	v_cos_f32_e32 v68, v57
	v_mul_f32_e32 v57, v87, v56
	v_mul_f32_e32 v56, v99, v56
	v_mov_b32_e32 v122, v81
	v_mov_b32_e32 v123, v80
	v_mov_b32_e32 v124, v109
	v_mov_b32_e32 v125, v108
	v_add_f32_e32 v66, v66, v67
	v_mul_f32_e32 v66, 0x3e38aa3b, v66
	v_cvt_pk_bf16_f32 v143, v79, v66
	v_mov_b32_e32 v78, v75
	v_mov_b32_e32 v79, v74
	s_waitcnt vmcnt(3)
	v_lshlrev_b32_e32 v82, 16, v91
	v_and_b32_e32 v84, 0xffff0000, v91
	s_waitcnt vmcnt(2)
	v_lshlrev_b32_e32 v83, 16, v95
	v_and_b32_e32 v85, 0xffff0000, v95
	v_mov_b32_e32 v76, v84
	v_mov_b32_e32 v77, v82
	v_pk_mul_f32 v[86:87], v[76:77], v[76:77]
	v_mov_b32_e32 v76, v85
	v_mov_b32_e32 v77, v83
	v_lshlrev_b32_e32 v113, 16, v94
	v_and_b32_e32 v91, 0xffff0000, v94
	v_pk_mul_f32 v[110:111], v[76:77], v[76:77]
	v_mov_b32_e32 v76, v91
	v_mov_b32_e32 v77, v113
	v_lshlrev_b32_e32 v115, 16, v93
	v_and_b32_e32 v117, 0xffff0000, v93
	v_pk_mul_f32 v[94:95], v[76:77], v[76:77]
	v_lshlrev_b32_e32 v114, 16, v89
	v_and_b32_e32 v116, 0xffff0000, v89
	v_mov_b32_e32 v76, v117
	v_mov_b32_e32 v77, v115
	v_lshlrev_b32_e32 v121, 16, v92
	v_and_b32_e32 v89, 0xffff0000, v92
	v_pk_mul_f32 v[118:119], v[76:77], v[76:77]
	v_mov_b32_e32 v76, v89
	v_mov_b32_e32 v77, v121
	v_pk_mul_f32 v[92:93], v[76:77], v[76:77]
	v_lshlrev_b32_e32 v120, 16, v88
	v_and_b32_e32 v88, 0xffff0000, v88
	v_lshlrev_b32_e32 v112, 16, v90
	v_and_b32_e32 v90, 0xffff0000, v90
	v_mov_b32_e32 v76, v73
	v_mul_f32_e32 v57, 0.15915494, v57
	v_sin_f32_e32 v66, v57
	v_cos_f32_e32 v67, v57
	s_add_u32 s0, s18, s0
	s_addc_u32 s1, s19, s1
	v_mul_f32_e32 v56, 0.15915494, v56
	v_sin_f32_e32 v57, v56
	v_cos_f32_e32 v56, v56
	s_waitcnt vmcnt(1)
	v_lshlrev_b32_e32 v154, 16, v101
	v_and_b32_e32 v158, 0xffff0000, v101
	s_waitcnt vmcnt(0)
	v_lshlrev_b32_e32 v163, 16, v104
	v_lshlrev_b32_e32 v162, 16, v100
	v_and_b32_e32 v101, 0xffff0000, v104
	v_and_b32_e32 v100, 0xffff0000, v100
	v_lshlrev_b32_e32 v155, 16, v105
	v_and_b32_e32 v159, 0xffff0000, v105
	v_pk_mul_f32 v[164:165], v[162:163], v[162:163]
	v_pk_mul_f32 v[104:105], v[100:101], v[100:101]
	v_pk_mul_f32 v[156:157], v[154:155], v[154:155]
	v_add_f32_e32 v77, v164, v104
	v_lshlrev_b32_e32 v151, 16, v106
	v_lshlrev_b32_e32 v150, 16, v102
	v_pk_mul_f32 v[160:161], v[158:159], v[158:159]
	v_add_f32_e32 v77, v156, v77
	v_lshlrev_b32_e32 v126, 16, v103
	v_and_b32_e32 v146, 0xffff0000, v103
	v_pk_mul_f32 v[152:153], v[150:151], v[150:151]
	v_and_b32_e32 v103, 0xffff0000, v106
	v_and_b32_e32 v102, 0xffff0000, v102
	v_add_f32_e32 v77, v160, v77
	v_lshlrev_b32_e32 v127, 16, v107
	v_and_b32_e32 v147, 0xffff0000, v107
	v_pk_mul_f32 v[106:107], v[102:103], v[102:103]
	v_add_f32_e32 v77, v152, v77
	v_pk_mul_f32 v[144:145], v[126:127], v[126:127]
	v_add_f32_e32 v77, v106, v77
	v_pk_mul_f32 v[148:149], v[146:147], v[146:147]
	v_add_f32_e32 v77, v144, v77
	v_add_f32_e32 v77, v148, v77
	v_add_f32_e32 v77, v165, v77
	v_add_f32_e32 v77, v105, v77
	v_add_f32_e32 v77, v157, v77
	v_add_f32_e32 v77, v161, v77
	v_add_f32_e32 v77, v153, v77
	v_add_f32_e32 v77, v107, v77
	v_add_f32_e32 v77, v145, v77
	v_add_f32_e32 v77, v149, v77
	v_fmac_f32_e32 v77, v120, v120
	v_fmac_f32_e32 v77, v88, v88
	v_fmac_f32_e32 v77, v114, v114
	v_fmac_f32_e32 v77, v116, v116
	v_fmac_f32_e32 v77, v112, v112
	v_fmac_f32_e32 v77, v90, v90
	v_add_f32_e32 v77, v87, v77
	v_add_f32_e32 v77, v86, v77
	v_add_f32_e32 v77, v93, v77
	v_add_f32_e32 v77, v92, v77
	v_add_f32_e32 v77, v119, v77
	v_add_f32_e32 v77, v118, v77
	v_add_f32_e32 v77, v95, v77
	v_add_f32_e32 v77, v94, v77
	v_add_f32_e32 v77, v111, v77
	v_add_f32_e32 v93, v110, v77
	ds_bpermute_b32 v94, v221, v93
	v_mov_b32_e32 v77, v72
	v_mov_b32_e32 v86, v71
	v_mov_b32_e32 v87, v70
	v_mov_b32_e32 v92, v69
	s_waitcnt lgkmcnt(0)
	v_add_f32_e32 v93, v93, v94
	v_fmamk_f32 v93, v93, 0x3c800000, v211
	v_mul_f32_e32 v94, 0x4b800000, v93
	v_cmp_gt_f32_e32 vcc, s33, v93
	v_mov_b32_e32 v95, v66
	s_lshl_b32 s52, s4, 8
	v_cndmask_b32_e32 v93, v93, v94, vcc
	v_rsq_f32_e32 v99, v93
	v_mov_b32_e32 v93, v68
	v_mov_b32_e32 v94, v67
	s_ashr_i32 s53, s52, 31
	v_mul_f32_e32 v104, 0x45800000, v99
	v_cndmask_b32_e32 v104, v99, v104, vcc
	v_pk_mul_f32 v[30:31], v[30:31], v[104:105] op_sel_hi:[1,0]
	v_pk_mul_f32 v[54:55], v[54:55], v[104:105] op_sel_hi:[1,0]
	v_pk_mul_f32 v[30:31], v[30:31], v[162:163]
	v_pk_mul_f32 v[54:55], v[54:55], v[120:121]
	v_pk_mul_f32 v[60:61], v[60:61], v[30:31]
	v_pk_mul_f32 v[30:31], v[42:43], v[30:31]
	v_pk_mul_f32 v[4:5], v[4:5], v[104:105] op_sel_hi:[1,0]
	v_add_f32_e32 v30, v30, v31
	v_mul_f32_e32 v42, 0x3e38aa3b, v30
	v_pk_mul_f32 v[30:31], v[122:123], v[54:55]
	v_pk_mul_f32 v[4:5], v[4:5], v[100:101]
	v_sub_f32_e32 v30, v30, v31
	v_mul_f32_e32 v43, 0x3e38aa3b, v30
	v_pk_mul_f32 v[30:31], v[80:81], v[54:55]
	v_pk_mul_f32 v[12:13], v[12:13], v[104:105] op_sel_hi:[1,0]
	v_add_f32_e32 v30, v30, v31
	v_mul_f32_e32 v54, 0x3e38aa3b, v30
	v_pk_mul_f32 v[30:31], v[44:45], v[4:5]
	v_pk_mul_f32 v[4:5], v[62:63], v[4:5]
	v_pk_mul_f32 v[12:13], v[12:13], v[88:89]
	v_add_f32_e32 v4, v4, v5
	v_sub_f32_e32 v30, v30, v31
	v_mul_f32_e32 v31, 0x3e38aa3b, v4
	v_pk_mul_f32 v[4:5], v[108:109], v[12:13]
	v_pk_mul_f32 v[28:29], v[28:29], v[104:105] op_sel_hi:[1,0]
	v_sub_f32_e32 v4, v4, v5
	v_mul_f32_e32 v44, 0x3e38aa3b, v4
	v_pk_mul_f32 v[4:5], v[124:125], v[12:13]
	v_pk_mul_f32 v[28:29], v[28:29], v[154:155]
	v_add_f32_e32 v4, v4, v5
	v_mul_f32_e32 v12, 0x3e38aa3b, v4
	v_pk_mul_f32 v[4:5], v[64:65], v[28:29]
	v_pk_mul_f32 v[52:53], v[52:53], v[104:105] op_sel_hi:[1,0]
	v_sub_f32_e32 v4, v4, v5
	v_mul_f32_e32 v13, 0x3e38aa3b, v4
	v_pk_mul_f32 v[4:5], v[46:47], v[28:29]
	v_lshlrev_b32_e32 v28, 2, v98
	global_load_dword v29, v28, s[14:15]
	v_pk_mul_f32 v[52:53], v[52:53], v[114:115]
	global_load_dword v28, v28, s[16:17]
	v_add_f32_e32 v4, v4, v5
	v_mul_f32_e32 v45, 0x3e38aa3b, v4
	v_pk_mul_f32 v[4:5], v[78:79], v[52:53]
	v_pk_mul_f32 v[6:7], v[6:7], v[104:105] op_sel_hi:[1,0]
	v_sub_f32_e32 v4, v4, v5
	v_mul_f32_e32 v46, 0x3e38aa3b, v4
	v_pk_mul_f32 v[4:5], v[74:75], v[52:53]
	v_pk_mul_f32 v[6:7], v[6:7], v[158:159]
	v_add_f32_e32 v4, v4, v5
	v_mul_f32_e32 v47, 0x3e38aa3b, v4
	v_pk_mul_f32 v[4:5], v[32:33], v[6:7]
	v_pk_mul_f32 v[14:15], v[14:15], v[104:105] op_sel_hi:[1,0]
	v_sub_f32_e32 v4, v4, v5
	v_mul_f32_e32 v32, 0x3e38aa3b, v4
	v_pk_mul_f32 v[4:5], v[16:17], v[6:7]
	v_pk_mul_f32 v[14:15], v[14:15], v[116:117]
	v_add_f32_e32 v4, v4, v5
	v_mul_f32_e32 v6, 0x3e38aa3b, v4
	v_pk_mul_f32 v[4:5], v[72:73], v[14:15]
	v_pk_mul_f32 v[22:23], v[22:23], v[104:105] op_sel_hi:[1,0]
	v_sub_f32_e32 v4, v4, v5
	v_mul_f32_e32 v7, 0x3e38aa3b, v4
	v_pk_mul_f32 v[4:5], v[76:77], v[14:15]
	v_pk_mul_f32 v[22:23], v[22:23], v[150:151]
	v_add_f32_e32 v4, v4, v5
	v_mul_f32_e32 v14, 0x3e38aa3b, v4
	v_pk_mul_f32 v[4:5], v[18:19], v[22:23]
	v_pk_mul_f32 v[50:51], v[50:51], v[104:105] op_sel_hi:[1,0]
	v_sub_f32_e32 v4, v4, v5
	v_mul_f32_e32 v15, 0x3e38aa3b, v4
	v_pk_mul_f32 v[4:5], v[34:35], v[22:23]
	v_pk_mul_f32 v[50:51], v[50:51], v[112:113]
	v_add_f32_e32 v4, v4, v5
	v_mul_f32_e32 v16, 0x3e38aa3b, v4
	v_pk_mul_f32 v[4:5], v[86:87], v[50:51]
	v_pk_mul_f32 v[0:1], v[0:1], v[104:105] op_sel_hi:[1,0]
	v_sub_f32_e32 v4, v4, v5
	v_mul_f32_e32 v17, 0x3e38aa3b, v4
	v_pk_mul_f32 v[4:5], v[70:71], v[50:51]
	v_pk_mul_f32 v[0:1], v[0:1], v[102:103]
	v_add_f32_e32 v4, v4, v5
	v_pk_mul_f32 v[8:9], v[8:9], v[104:105] op_sel_hi:[1,0]
	v_mul_f32_e32 v18, 0x3e38aa3b, v4
	v_pk_mul_f32 v[4:5], v[36:37], v[0:1]
	v_pk_mul_f32 v[0:1], v[20:21], v[0:1]
	v_pk_mul_f32 v[8:9], v[8:9], v[90:91]
	v_add_f32_e32 v0, v0, v1
	v_sub_f32_e32 v4, v4, v5
	v_mul_f32_e32 v5, 0x3e38aa3b, v0
	v_pk_mul_f32 v[0:1], v[68:69], v[8:9]
	v_pk_mul_f32 v[58:59], v[58:59], v[104:105] op_sel_hi:[1,0]
	v_sub_f32_e32 v0, v0, v1
	v_mul_f32_e32 v19, 0x3e38aa3b, v0
	v_pk_mul_f32 v[0:1], v[92:93], v[8:9]
	v_pk_mul_f32 v[58:59], v[58:59], v[126:127]
	v_add_f32_e32 v0, v0, v1
	v_mul_f32_e32 v8, 0x3e38aa3b, v0
	v_pk_mul_f32 v[0:1], v[24:25], v[58:59]
	v_pk_mul_f32 v[48:49], v[48:49], v[104:105] op_sel_hi:[1,0]
	v_sub_f32_e32 v0, v0, v1
	v_mul_f32_e32 v9, 0x3e38aa3b, v0
	v_pk_mul_f32 v[0:1], v[38:39], v[58:59]
	v_pk_mul_f32 v[48:49], v[48:49], v[82:83]
	v_add_f32_e32 v0, v0, v1
	v_mul_f32_e32 v20, 0x3e38aa3b, v0
	v_pk_mul_f32 v[0:1], v[94:95], v[48:49]
	v_pk_mul_f32 v[2:3], v[2:3], v[104:105] op_sel_hi:[1,0]
	v_sub_f32_e32 v0, v0, v1
	v_mul_f32_e32 v21, 0x3e38aa3b, v0
	v_pk_mul_f32 v[0:1], v[66:67], v[48:49]
	v_pk_mul_f32 v[2:3], v[2:3], v[146:147]
	v_add_f32_e32 v0, v0, v1
	v_mul_f32_e32 v22, 0x3e38aa3b, v0
	v_pk_mul_f32 v[0:1], v[40:41], v[2:3]
	v_pk_mul_f32 v[10:11], v[10:11], v[104:105] op_sel_hi:[1,0]
	v_sub_f32_e32 v0, v0, v1
	v_mul_f32_e32 v23, 0x3e38aa3b, v0
	v_pk_mul_f32 v[0:1], v[26:27], v[2:3]
	global_load_dword v2, v199, s[0:1]
	v_pk_mul_f32 v[10:11], v[10:11], v[84:85]
	v_add_f32_e32 v0, v0, v1
	v_mul_f32_e32 v3, 0x3e38aa3b, v0
	v_pk_mul_f32 v[0:1], v[56:57], v[10:11]
	v_cmp_lt_i32_e32 vcc, v215, v209
	v_sub_f32_e32 v0, v0, v1
	v_mul_f32_e32 v24, 0x3e38aa3b, v0
	v_mov_b32_e32 v0, v57
	v_mov_b32_e32 v1, v56
	v_pk_mul_f32 v[0:1], v[0:1], v[10:11]
	v_mul_f32_e32 v4, 0x3e38aa3b, v4
	v_add_f32_e32 v0, v0, v1
	v_cndmask_b32_e32 v1, v207, v215, vcc
	v_mul_f32_e32 v10, 0x3e38aa3b, v0
	s_waitcnt vmcnt(2)
	v_and_b32_e32 v0, 0x7fffffff, v29
	v_lshlrev_b32_e32 v223, 2, v1
	ds_bpermute_b32 v0, v223, v0
	s_waitcnt vmcnt(1)
	v_and_b32_e32 v1, 0x7fffffff, v28
	ds_bpermute_b32 v1, v223, v1
	v_cmp_lt_i32_e32 vcc, v216, v209
	v_cvt_pk_bf16_f32 v146, v15, v4
	v_cvt_pk_bf16_f32 v147, v9, v23
	s_waitcnt lgkmcnt(1)
	v_max_f32_e32 v0, v0, v0
	v_max_f32_e64 v4, |v29|, |v29|
	v_cndmask_b32_e32 v9, v207, v216, vcc
	v_max_f32_e32 v0, v4, v0
	v_lshlrev_b32_e32 v224, 2, v9
	s_waitcnt lgkmcnt(0)
	v_max_f32_e32 v1, v1, v1
	v_max_f32_e64 v4, |v28|, |v28|
	ds_bpermute_b32 v9, v224, v0
	v_max_f32_e32 v1, v4, v1
	ds_bpermute_b32 v4, v224, v1
	v_cvt_pk_bf16_f32 v150, v16, v5
	v_cmp_lt_i32_e32 vcc, v217, v209
	s_waitcnt lgkmcnt(1)
	v_max_f32_e32 v5, v9, v9
	v_max_f32_e32 v0, v0, v5
	v_cndmask_b32_e32 v5, v207, v217, vcc
	s_waitcnt lgkmcnt(0)
	v_max_f32_e32 v4, v4, v4
	v_lshlrev_b32_e32 v5, 2, v5
	v_cvt_pk_bf16_f32 v149, v45, v6
	ds_bpermute_b32 v6, v5, v0
	v_max_f32_e32 v1, v1, v4
	ds_bpermute_b32 v4, v5, v1
	v_cvt_pk_bf16_f32 v151, v20, v3
	v_cmp_lt_i32_e32 vcc, v218, v209
	s_waitcnt lgkmcnt(1)
	v_max_f32_e32 v3, v6, v6
	v_max_f32_e32 v0, v0, v3
	s_waitcnt lgkmcnt(0)
	v_max_f32_e32 v3, v4, v4
	v_cndmask_b32_e32 v4, v207, v218, vcc
	v_lshlrev_b32_e32 v4, 2, v4
	ds_bpermute_b32 v5, v4, v0
	v_max_f32_e32 v1, v1, v3
	ds_bpermute_b32 v3, v4, v1
	v_cmp_lt_i32_e32 vcc, v219, v209
	s_mov_b32 s0, 0x3fb8aa3b
	s_waitcnt lgkmcnt(1)
	v_max_f32_e32 v4, v5, v5
	v_max_f32_e32 v0, v0, v4
	v_cndmask_b32_e32 v4, v207, v219, vcc
	s_waitcnt lgkmcnt(0)
	v_max_f32_e32 v3, v3, v3
	v_lshlrev_b32_e32 v4, 2, v4
	ds_bpermute_b32 v5, v4, v0
	v_max_f32_e32 v1, v1, v3
	ds_bpermute_b32 v3, v4, v1
	v_ashrrev_i32_e32 v200, 2, v96
	v_ashrrev_i32_e32 v201, 31, v200
	s_waitcnt lgkmcnt(1)
	v_max_f32_e32 v4, v5, v5
	v_max_f32_e32 v0, v0, v4
	s_waitcnt lgkmcnt(0)
	v_max_f32_e32 v3, v3, v3
	ds_bpermute_b32 v4, v221, v0
	v_max_f32_e32 v1, v1, v3
	ds_bpermute_b32 v3, v221, v1
	v_bfe_u32 v225, v96, 1, 1
	v_and_b32_e32 v226, 1, v96
	s_waitcnt lgkmcnt(1)
	v_max_f32_e32 v4, v4, v4
	v_max_f32_e32 v0, v0, v4
	s_waitcnt lgkmcnt(0)
	v_max_f32_e32 v3, v3, v3
	v_max_f32_e32 v1, v1, v3
	v_mul_f32_e32 v0, 0x41000000, v0
	v_mul_f32_e32 v0, v1, v0
	v_mul_f32_e32 v0, 0x3fb8aa3b, v0
	s_waitcnt vmcnt(0)
	v_mul_f32_e32 v235, 0x3fb8aa3b, v2
	v_fmamk_f32 v0, v0, 0x3f828f5c, v212
	v_max_f32_e32 v4, v0, v235
	v_fma_f32 v5, v2, s0, -v4
	s_add_u32 s0, s52, 0x10000
	s_addc_u32 s1, s53, 0
	v_lshl_add_u64 v[0:1], s[0:1], 0, v[200:201]
	v_mov_b64_e32 v[2:3], s[28:29]
	v_mad_u64_u32 v[2:3], s[0:1], v0, s25, v[2:3]
	v_mad_i32_i24 v3, v1, s25, v3
	s_lshl_b32 s8, s2, 7
	v_lshl_add_u64 v[0:1], v[2:3], 0, s[8:9]
	v_lshlrev_b32_e32 v198, 6, v225
	v_and_b32_e32 v6, 3, v96
	v_lshl_add_u64 v[2:3], v[0:1], 0, v[198:199]
	v_lshlrev_b32_e32 v198, 4, v226
	v_lshl_add_u64 v[2:3], v[2:3], 0, v[198:199]
	v_lshlrev_b32_e32 v198, 5, v6
	v_lshl_add_u64 v[0:1], v[0:1], 0, v[198:199]
	v_mov_b64_e32 v[88:89], v[176:177]
	v_mov_b64_e32 v[90:91], v[178:179]
	v_mov_b64_e32 v[92:93], v[180:181]
	v_mov_b64_e32 v[94:95], v[182:183]
	v_mov_b64_e32 v[80:81], v[184:185]
	v_mov_b64_e32 v[82:83], v[186:187]
	v_mov_b64_e32 v[84:85], v[188:189]
	v_mov_b64_e32 v[86:87], v[190:191]
	v_exp_f32_e32 v0, v5
	v_cmp_gt_f32_e32 vcc, s31, v4
	v_cmp_gt_u32_e64 s[0:1], 32, v98
	s_ashr_i32 s5, s4, 31
	v_cndmask_b32_e32 v0, 1.0, v0, vcc
	s_lshl_b32 s85, s7, 1
	v_cndmask_b32_e64 v227, 0, v0, s[0:1]
	s_add_i32 s84, s72, -2
	s_lshl_b64 s[0:1], s[4:5], 12
	s_or_b32 s86, s85, 1
	v_lshlrev_b32_e32 v1, 4, v96
	v_lshl_add_u32 v0, v225, 13, 0
	s_add_u32 s52, s52, 0x10080
	v_and_b32_e32 v1, 0xc0, v1
	v_lshlrev_b32_e32 v2, 1, v96
	v_sub_f32_e32 v60, v60, v61
	v_mul_f32_e32 v30, 0x3e38aa3b, v30
	v_cvt_pk_bf16_f32 v154, v17, v19
	v_cvt_pk_bf16_f32 v155, v21, v24
	v_cvt_pk_bf16_f32 v157, v47, v14
	v_cvt_pk_bf16_f32 v158, v18, v8
	v_cvt_pk_bf16_f32 v159, v22, v10
	v_lshlrev_b32_e32 v16, 5, v225
	v_lshlrev_b32_e32 v18, 3, v226
	v_lshlrev_b32_e32 v20, 4, v6
	v_lshl_add_u32 v17, v226, 11, v0
	v_lshlrev_b32_e32 v19, 4, v200
	v_lshl_add_u32 v21, v200, 6, v0
	v_lshlrev_b32_e32 v22, 5, v226
	v_lshlrev_b32_e32 v0, 4, v222
	s_addc_u32 s53, s53, 0
	v_lshl_or_b32 v1, v97, 8, v1
	v_and_b32_e32 v2, 32, v2
	v_lshlrev_b32_e32 v3, 3, v6
	v_mov_b32_e32 v14, v199
	v_mov_b32_e32 v15, v199
	v_mul_f32_e32 v60, 0x3e38aa3b, v60
	v_cvt_pk_bf16_f32 v144, v60, v30
	v_cvt_pk_bf16_f32 v145, v13, v32
	v_cvt_pk_bf16_f32 v148, v42, v31
	v_cvt_pk_bf16_f32 v152, v43, v44
	v_cvt_pk_bf16_f32 v153, v46, v7
	v_cvt_pk_bf16_f32 v156, v54, v12
	v_cmp_ngt_f32_e64 s[2:3], s31, v4
	v_cndmask_b32_e64 v48, 0, -v4, vcc
	v_cmp_gt_u32_e64 s[4:5], 2, v6
	v_or_b32_e32 v229, s6, v222
	s_add_u32 s54, s28, s8
	v_or3_b32 v231, v1, v2, v3
	v_lshl_or_b32 v232, v97, 11, v0
	v_mov_b32_e32 v0, v199
	v_mov_b32_e32 v1, v199
	v_mov_b32_e32 v2, v199
	v_mov_b32_e32 v3, v199
	v_mov_b32_e32 v4, v199
	v_mov_b32_e32 v5, v199
	v_mov_b32_e32 v6, v199
	v_mov_b32_e32 v7, v199
	v_mov_b32_e32 v8, v199
	v_mov_b32_e32 v9, v199
	v_mov_b32_e32 v10, v199
	v_mov_b32_e32 v11, v199
	v_mov_b32_e32 v12, v199
	v_mov_b32_e32 v13, v199
	v_lshlrev_b32_e32 v198, 1, v16
	v_lshlrev_b32_e32 v202, 1, v18
	v_lshlrev_b32_e32 v204, 1, v20
	v_add_u32_e32 v233, v17, v19
	v_add_u32_e32 v234, v21, v22
	v_mov_b64_e32 v[30:31], v[14:15]
	v_mov_b64_e32 v[46:47], v[14:15]
	v_mov_b64_e32 v[78:79], v[14:15]
	s_mov_b32 s73, 0
	v_lshlrev_b32_e32 v228, 2, v97
	v_mov_b32_e32 v49, v48
	v_mov_b32_e32 v50, v48
	v_mov_b32_e32 v51, v48
	v_mov_b32_e32 v52, v48
	v_mov_b32_e32 v53, v48
	v_mov_b32_e32 v54, v48
	v_mov_b32_e32 v55, v48
	v_mov_b32_e32 v56, v48
	v_mov_b32_e32 v57, v48
	v_mov_b32_e32 v58, v48
	v_mov_b32_e32 v59, v48
	v_mov_b32_e32 v60, v48
	v_mov_b32_e32 v61, v48
	v_mov_b32_e32 v62, v48
	v_mov_b32_e32 v63, v48
	v_or_b32_e32 v230, 32, v229
	s_addc_u32 s55, s29, 0
	v_mov_b32_e32 v113, v235
	v_mov_b32_e32 v112, v227
	v_mov_b64_e32 v[28:29], v[12:13]
	v_mov_b64_e32 v[26:27], v[10:11]
	v_mov_b64_e32 v[24:25], v[8:9]
	v_mov_b64_e32 v[22:23], v[6:7]
	v_mov_b64_e32 v[20:21], v[4:5]
	v_mov_b64_e32 v[18:19], v[2:3]
	v_mov_b64_e32 v[16:17], v[0:1]
	v_mov_b64_e32 v[44:45], v[12:13]
	v_mov_b64_e32 v[42:43], v[10:11]
	v_mov_b64_e32 v[40:41], v[8:9]
	v_mov_b64_e32 v[38:39], v[6:7]
	v_mov_b64_e32 v[36:37], v[4:5]
	v_mov_b64_e32 v[34:35], v[2:3]
	v_mov_b64_e32 v[32:33], v[0:1]
	v_mov_b64_e32 v[76:77], v[12:13]
	v_mov_b64_e32 v[74:75], v[10:11]
	v_mov_b64_e32 v[72:73], v[8:9]
	v_mov_b64_e32 v[70:71], v[6:7]
	v_mov_b64_e32 v[68:69], v[4:5]
	v_mov_b64_e32 v[66:67], v[2:3]
	v_mov_b64_e32 v[64:65], v[0:1]
	s_mov_b64 s[6:7], -1
	s_cmp_lt_u32 s73, 2
	s_mov_b32 s8, 0
	s_cbranch_scc1 .LBB0_408
